# attention row-max: canonicalising self-max instructions removed (8 fewer VALU per two KV tiles) on top of the bracketed top-k version
# baseline (speedup 1.0000x reference)
.LBB0_799:
	v_add_u32_e32 v0, s1, v230
	ds_read_b64_tr_b16 v[6:7], v0 offset:24576
	ds_read_b64_tr_b16 v[8:9], v0 offset:25088
	v_add_f32_e32 v2, v80, v81
	v_add_f32_e32 v2, v82, v2
	v_add_f32_e32 v2, v83, v2
	v_add_f32_e32 v2, v84, v2
	v_add_f32_e32 v10, v85, v2
	v_cvt_pk_bf16_f32 v156, v80, v81
	v_cvt_pk_bf16_f32 v157, v82, v83
	s_waitcnt lgkmcnt(9)
	v_mfma_f32_32x32x16_bf16 v[96:111], v[188:191], v[148:151], v[48:63]
	ds_read_b64_tr_b16 v[2:3], v0 offset:28672
	ds_read_b64_tr_b16 v[4:5], v0 offset:29184
	s_waitcnt lgkmcnt(10)
	v_mfma_f32_32x32x16_bf16 v[48:63], v[184:187], v[148:151], v[48:63]
	v_add_f32_e32 v10, v86, v10
	v_add_f32_e32 v10, v87, v10
	v_add_f32_e32 v10, v88, v10
	v_add_f32_e32 v14, v89, v10
	v_cvt_pk_bf16_f32 v158, v84, v85
	v_cvt_pk_bf16_f32 v159, v86, v87
	ds_read_b64_tr_b16 v[10:11], v0 offset:25600
	ds_read_b64_tr_b16 v[12:13], v0 offset:26112
	v_add_f32_e32 v14, v90, v14
	v_add_f32_e32 v14, v91, v14
	v_add_f32_e32 v14, v92, v14
	v_add_f32_e32 v14, v93, v14
	v_cvt_pk_bf16_f32 v152, v88, v89
	v_cvt_pk_bf16_f32 v153, v90, v91
	s_waitcnt lgkmcnt(11)
	v_mfma_f32_32x32x16_bf16 v[96:111], v[180:183], v[136:139], v[96:111]
	ds_read_b64_tr_b16 v[112:113], v0 offset:29696
	ds_read_b64_tr_b16 v[114:115], v0 offset:30208
	s_waitcnt lgkmcnt(12)
	v_mfma_f32_32x32x16_bf16 v[48:63], v[176:179], v[136:139], v[48:63]
	v_add_f32_e32 v14, v94, v14
	v_add_f32_e32 v14, v95, v14
	v_add_f32_e32 v14, v64, v14
	v_add_f32_e32 v14, v65, v14
	v_cvt_pk_bf16_f32 v154, v92, v93
	v_cvt_pk_bf16_f32 v155, v94, v95
	ds_read_b64_tr_b16 v[116:117], v0 offset:26624
	ds_read_b64_tr_b16 v[118:119], v0 offset:27136
	v_add_f32_e32 v14, v66, v14
	v_add_f32_e32 v14, v67, v14
	v_add_f32_e32 v14, v68, v14
	v_add_f32_e32 v14, v69, v14
	v_cvt_pk_bf16_f32 v144, v64, v65
	v_cvt_pk_bf16_f32 v145, v66, v67
	s_waitcnt lgkmcnt(13)
	v_mfma_f32_32x32x16_bf16 v[96:111], v[172:175], v[132:135], v[96:111]
	ds_read_b64_tr_b16 v[120:121], v0 offset:30720
	ds_read_b64_tr_b16 v[122:123], v0 offset:31232
	s_waitcnt lgkmcnt(14)
	v_mfma_f32_32x32x16_bf16 v[48:63], v[168:171], v[132:135], v[48:63]
	v_add_f32_e32 v14, v70, v14
	v_add_f32_e32 v14, v71, v14
	v_add_f32_e32 v14, v72, v14
	v_add_f32_e32 v14, v73, v14
	v_cvt_pk_bf16_f32 v146, v68, v69
	v_cvt_pk_bf16_f32 v147, v70, v71
	ds_read_b64_tr_b16 v[124:125], v0 offset:27648
	ds_read_b64_tr_b16 v[126:127], v0 offset:28160
	v_add_f32_e32 v14, v74, v14
	v_add_f32_e32 v14, v75, v14
	v_add_f32_e32 v14, v76, v14
	v_add_f32_e32 v14, v77, v14
	v_cvt_pk_bf16_f32 v140, v72, v73
	v_cvt_pk_bf16_f32 v141, v74, v75
	s_waitcnt lgkmcnt(14)
	v_mfma_f32_32x32x16_bf16 v[96:111], v[164:167], v[128:131], v[96:111]
	ds_read_b64_tr_b16 v[132:133], v0 offset:31744
	ds_read_b64_tr_b16 v[134:135], v0 offset:32256
	v_mfma_f32_32x32x16_bf16 v[48:63], v[160:163], v[128:131], v[48:63]
	v_add_f32_e32 v0, v78, v14
	v_add_f32_e32 v0, v79, v0
	v_add_f32_e32 v0, 0, v0
	v_cvt_pk_bf16_f32 v142, v76, v77
	v_cvt_pk_bf16_f32 v143, v78, v79
	v_or_b32_e32 v15, 0xe0, v223
	v_or_b32_e32 v14, 0xc0, v223
	v_cmp_le_i32_e32 vcc, v15, v225
	s_mov_b32 s0, 0x41000000
	v_add_f32_e32 v0, v232, v0
	s_nop 1
	v_cndmask_b32_e32 v48, v215, v48, vcc
	v_cmp_lt_i32_e32 vcc, v14, v225
	s_nop 1
	v_cndmask_b32_e32 v65, v215, v97, vcc
	v_cmp_le_i32_e32 vcc, v14, v225
	v_or_b32_e32 v14, 0xe1, v223
	s_nop 0
	v_cndmask_b32_e32 v64, v215, v96, vcc
	v_cmp_le_i32_e32 vcc, v14, v225
	v_or_b32_e32 v14, 0xc2, v223
	v_max_f32_e32 v15, v64, v64
	v_cndmask_b32_e32 v49, v215, v49, vcc
	v_cmp_le_i32_e32 vcc, v14, v225
	v_or_b32_e32 v14, 0xe2, v223
	s_nop 0
	v_cndmask_b32_e32 v66, v215, v98, vcc
	v_cmp_le_i32_e32 vcc, v14, v225
	v_or_b32_e32 v14, 0xc3, v223
	s_nop 0
	v_cndmask_b32_e32 v50, v215, v50, vcc
	v_cmp_le_i32_e32 vcc, v14, v225
	v_or_b32_e32 v14, 0xe3, v223
	s_nop 0
	v_cndmask_b32_e32 v67, v215, v99, vcc
	v_cmp_le_i32_e32 vcc, v14, v225
	v_or_b32_e32 v14, 0xc8, v223
	s_nop 0
	v_cndmask_b32_e32 v51, v215, v51, vcc
	v_cmp_le_i32_e32 vcc, v14, v225
	v_or_b32_e32 v14, 0xe8, v223
	s_nop 0
	v_cndmask_b32_e32 v68, v215, v100, vcc
	v_cmp_le_i32_e32 vcc, v14, v225
	v_or_b32_e32 v14, 0xc9, v223
	s_nop 0
	v_cndmask_b32_e32 v52, v215, v52, vcc
	v_cmp_le_i32_e32 vcc, v14, v225
	v_or_b32_e32 v14, 0xe9, v223
	s_nop 0
	v_cndmask_b32_e32 v69, v215, v101, vcc
	v_cmp_le_i32_e32 vcc, v14, v225
	v_or_b32_e32 v14, 0xca, v223
	s_nop 0
	v_cndmask_b32_e32 v53, v215, v53, vcc
	v_cmp_le_i32_e32 vcc, v14, v225
	v_or_b32_e32 v14, 0xea, v223
	s_nop 0
	v_cndmask_b32_e32 v70, v215, v102, vcc
	v_cmp_le_i32_e32 vcc, v14, v225
	v_or_b32_e32 v14, 0xcb, v223
	s_nop 0
	v_cndmask_b32_e32 v54, v215, v54, vcc
	v_cmp_le_i32_e32 vcc, v14, v225
	v_or_b32_e32 v14, 0xeb, v223
	s_nop 0
	v_cndmask_b32_e32 v71, v215, v103, vcc
	v_cmp_le_i32_e32 vcc, v14, v225
	v_or_b32_e32 v14, 0xd0, v223
	s_nop 0
	v_cndmask_b32_e32 v55, v215, v55, vcc
	v_cmp_le_i32_e32 vcc, v14, v225
	v_or_b32_e32 v14, 0xf0, v223
	s_nop 0
	v_cndmask_b32_e32 v72, v215, v104, vcc
	v_cmp_le_i32_e32 vcc, v14, v225
	v_or_b32_e32 v14, 0xd1, v223
	s_nop 0
	v_cndmask_b32_e32 v56, v215, v56, vcc
	v_cmp_le_i32_e32 vcc, v14, v225
	v_or_b32_e32 v14, 0xf1, v223
	s_nop 0
	v_cndmask_b32_e32 v73, v215, v105, vcc
	v_cmp_le_i32_e32 vcc, v14, v225
	v_or_b32_e32 v14, 0xd2, v223
	s_nop 0
	v_cndmask_b32_e32 v57, v215, v57, vcc
	v_cmp_le_i32_e32 vcc, v14, v225
	v_or_b32_e32 v14, 0xf2, v223
	s_nop 0
	v_cndmask_b32_e32 v74, v215, v106, vcc
	v_cmp_le_i32_e32 vcc, v14, v225
	v_or_b32_e32 v14, 0xd3, v223
	s_nop 0
	v_cndmask_b32_e32 v58, v215, v58, vcc
	v_cmp_le_i32_e32 vcc, v14, v225
	v_or_b32_e32 v14, 0xf3, v223
	s_nop 0
	v_cndmask_b32_e32 v75, v215, v107, vcc
	v_cmp_le_i32_e32 vcc, v14, v225
	v_or_b32_e32 v14, 0xd8, v223
	s_nop 0
	v_cndmask_b32_e32 v59, v215, v59, vcc
	v_cmp_le_i32_e32 vcc, v14, v225
	v_or_b32_e32 v14, 0xf8, v223
	s_nop 0
	v_cndmask_b32_e32 v76, v215, v108, vcc
	v_cmp_le_i32_e32 vcc, v14, v225
	v_or_b32_e32 v14, 0xd9, v223
	s_nop 0
	v_cndmask_b32_e32 v60, v215, v60, vcc
	v_cmp_le_i32_e32 vcc, v14, v225
	v_or_b32_e32 v14, 0xf9, v223
	s_nop 0
	v_cndmask_b32_e32 v77, v215, v109, vcc
	v_cmp_le_i32_e32 vcc, v14, v225
	v_or_b32_e32 v14, 0xda, v223
	s_nop 0
	v_cndmask_b32_e32 v61, v215, v61, vcc
	v_cmp_le_i32_e32 vcc, v14, v225
	v_or_b32_e32 v14, 0xfa, v223
	s_nop 0
	v_cndmask_b32_e32 v78, v215, v110, vcc
	v_cmp_le_i32_e32 vcc, v14, v225
	v_or_b32_e32 v14, 0xdb, v223
	s_nop 0
	v_cndmask_b32_e32 v62, v215, v62, vcc
	v_cmp_le_i32_e32 vcc, v14, v225
	v_or_b32_e32 v14, 0xfb, v223
	s_nop 0
	v_cndmask_b32_e32 v79, v215, v111, vcc
	v_cmp_le_i32_e32 vcc, v14, v225
	v_max_f32_e32 v14, v65, v65
	v_max_f32_e32 v14, v15, v14
	v_max3_f32 v15, v66, v67, v49
	v_max3_f32 v14, v14, v48, v50
	v_max3_f32 v14, v14, v51, v68
	v_max3_f32 v15, v15, v70, v71
	v_max3_f32 v14, v14, v69, v52
	v_max3_f32 v15, v15, v54, v55
	v_max3_f32 v14, v14, v53, v72
	v_max3_f32 v15, v15, v74, v75
	v_max3_f32 v14, v14, v73, v56
	v_max3_f32 v15, v15, v58, v59
	v_cndmask_b32_e32 v63, v215, v63, vcc
	v_max3_f32 v14, v14, v57, v76
	v_max3_f32 v15, v15, v78, v79
	v_max3_f32 v14, v14, v77, v60
	v_max3_f32 v15, v15, v62, v63
	v_max3_f32 v14, v14, v61, v15
	v_mov_b32_e32 v15, v14
	s_nop 1
	v_permlane32_swap_b32_e32 v14, v15
	v_max_f32_e32 v14, v14, v15
	v_cmp_lt_f32_e32 vcc, s0, v14
	s_cmp_lg_u64 vcc, 0
	s_cselect_b64 s[4:5], -1, 0
	s_cbranch_vccnz .LBB0_1222

.LBB0_890:
	v_add_f32_e32 v15, v232, v14
	v_max_f32_e32 v14, v112, v113
	v_max3_f32 v76, v114, v115, v97
	v_max3_f32 v14, v14, v96, v98
	v_max3_f32 v14, v14, v99, v116
	v_max3_f32 v76, v76, v118, v119
	v_max3_f32 v14, v14, v117, v100
	v_max3_f32 v76, v76, v102, v103
	v_max3_f32 v14, v14, v101, v120
	v_max3_f32 v76, v76, v122, v123
	v_max3_f32 v14, v14, v121, v104
	v_max3_f32 v76, v76, v106, v107
	v_max3_f32 v14, v14, v105, v124
	v_max3_f32 v76, v76, v126, v127
	v_max3_f32 v14, v14, v125, v108
	v_max3_f32 v76, v76, v110, v111
	v_max3_f32 v14, v14, v109, v76
	v_mov_b32_e32 v76, v14
	s_nop 1
	v_permlane32_swap_b32_e32 v14, v76
	v_max_f32_e32 v14, v14, v76
	s_mov_b32 s6, 0x41000000
	v_cmp_lt_f32_e32 vcc, s6, v14
	s_cmp_lg_u64 vcc, 0
	s_cselect_b64 s[6:7], -1, 0
	s_cbranch_vccnz .LBB0_928

.LBB0_905:
	v_add_f32_e32 v232, v15, v96
	v_max_f32_e32 v15, v80, v81
	v_max3_f32 v96, v82, v83, v65
	v_max3_f32 v15, v15, v64, v66
	v_max3_f32 v15, v15, v67, v84
	v_max3_f32 v96, v96, v86, v87
	v_max3_f32 v15, v15, v85, v68
	v_max3_f32 v96, v96, v70, v71
	v_max3_f32 v15, v15, v69, v88
	v_max3_f32 v96, v96, v90, v91
	v_max3_f32 v15, v15, v89, v72
	v_max3_f32 v96, v96, v74, v75
	v_max3_f32 v15, v15, v73, v92
	v_max3_f32 v96, v96, v94, v95
	v_max3_f32 v15, v15, v93, v76
	v_max3_f32 v96, v96, v78, v79
	v_max3_f32 v15, v15, v77, v96
	v_mov_b32_e32 v96, v15
	s_nop 1
	v_permlane32_swap_b32_e32 v15, v96
	v_max_f32_e32 v15, v15, v96
	s_mov_b32 s2, 0x41000000
	v_cmp_lt_f32_e32 vcc, s2, v15
	s_cmp_lg_u64 vcc, 0
	s_cselect_b64 s[22:23], -1, 0
	s_cbranch_vccnz .LBB0_931

.LBB0_2420:
	v_add_u32_e32 v0, s0, v231
	ds_read_b64_tr_b16 v[6:7], v0 offset:24576
	ds_read_b64_tr_b16 v[8:9], v0 offset:25088
	v_add_f32_e32 v2, v80, v81
	v_add_f32_e32 v2, v82, v2
	v_add_f32_e32 v2, v83, v2
	v_add_f32_e32 v2, v84, v2
	v_add_f32_e32 v10, v85, v2
	v_cvt_pk_bf16_f32 v156, v80, v81
	v_cvt_pk_bf16_f32 v157, v82, v83
	s_waitcnt lgkmcnt(9)
	v_mfma_f32_32x32x16_bf16 v[96:111], v[188:191], v[148:151], v[48:63]
	ds_read_b64_tr_b16 v[2:3], v0 offset:28672
	ds_read_b64_tr_b16 v[4:5], v0 offset:29184
	s_waitcnt lgkmcnt(10)
	v_mfma_f32_32x32x16_bf16 v[48:63], v[184:187], v[148:151], v[48:63]
	v_add_f32_e32 v10, v86, v10
	v_add_f32_e32 v10, v87, v10
	v_add_f32_e32 v10, v88, v10
	v_add_f32_e32 v14, v89, v10
	v_cvt_pk_bf16_f32 v158, v84, v85
	v_cvt_pk_bf16_f32 v159, v86, v87
	ds_read_b64_tr_b16 v[10:11], v0 offset:25600
	ds_read_b64_tr_b16 v[12:13], v0 offset:26112
	v_add_f32_e32 v14, v90, v14
	v_add_f32_e32 v14, v91, v14
	v_add_f32_e32 v14, v92, v14
	v_add_f32_e32 v14, v93, v14
	v_cvt_pk_bf16_f32 v152, v88, v89
	v_cvt_pk_bf16_f32 v153, v90, v91
	s_waitcnt lgkmcnt(11)
	v_mfma_f32_32x32x16_bf16 v[96:111], v[180:183], v[136:139], v[96:111]
	ds_read_b64_tr_b16 v[112:113], v0 offset:29696
	ds_read_b64_tr_b16 v[114:115], v0 offset:30208
	s_waitcnt lgkmcnt(12)
	v_mfma_f32_32x32x16_bf16 v[48:63], v[176:179], v[136:139], v[48:63]
	v_add_f32_e32 v14, v94, v14
	v_add_f32_e32 v14, v95, v14
	v_add_f32_e32 v14, v64, v14
	v_add_f32_e32 v14, v65, v14
	v_cvt_pk_bf16_f32 v154, v92, v93
	v_cvt_pk_bf16_f32 v155, v94, v95
	ds_read_b64_tr_b16 v[116:117], v0 offset:26624
	ds_read_b64_tr_b16 v[118:119], v0 offset:27136
	v_add_f32_e32 v14, v66, v14
	v_add_f32_e32 v14, v67, v14
	v_add_f32_e32 v14, v68, v14
	v_add_f32_e32 v14, v69, v14
	v_cvt_pk_bf16_f32 v144, v64, v65
	v_cvt_pk_bf16_f32 v145, v66, v67
	s_waitcnt lgkmcnt(13)
	v_mfma_f32_32x32x16_bf16 v[96:111], v[172:175], v[132:135], v[96:111]
	ds_read_b64_tr_b16 v[120:121], v0 offset:30720
	ds_read_b64_tr_b16 v[122:123], v0 offset:31232
	s_waitcnt lgkmcnt(14)
	v_mfma_f32_32x32x16_bf16 v[48:63], v[168:171], v[132:135], v[48:63]
	v_add_f32_e32 v14, v70, v14
	v_add_f32_e32 v14, v71, v14
	v_add_f32_e32 v14, v72, v14
	v_add_f32_e32 v14, v73, v14
	v_cvt_pk_bf16_f32 v146, v68, v69
	v_cvt_pk_bf16_f32 v147, v70, v71
	ds_read_b64_tr_b16 v[124:125], v0 offset:27648
	ds_read_b64_tr_b16 v[126:127], v0 offset:28160
	v_add_f32_e32 v14, v74, v14
	v_add_f32_e32 v14, v75, v14
	v_add_f32_e32 v14, v76, v14
	v_add_f32_e32 v14, v77, v14
	v_cvt_pk_bf16_f32 v140, v72, v73
	v_cvt_pk_bf16_f32 v141, v74, v75
	s_waitcnt lgkmcnt(14)
	v_mfma_f32_32x32x16_bf16 v[96:111], v[164:167], v[128:131], v[96:111]
	ds_read_b64_tr_b16 v[132:133], v0 offset:31744
	ds_read_b64_tr_b16 v[134:135], v0 offset:32256
	v_mfma_f32_32x32x16_bf16 v[48:63], v[160:163], v[128:131], v[48:63]
	v_add_f32_e32 v0, v78, v14
	v_add_f32_e32 v0, v79, v0
	v_add_f32_e32 v0, 0, v0
	v_cvt_pk_bf16_f32 v142, v76, v77
	v_cvt_pk_bf16_f32 v143, v78, v79
	v_or_b32_e32 v15, 0xe0, v224
	v_or_b32_e32 v14, 0xc0, v224
	v_cmp_le_i32_e32 vcc, v15, v226
	v_add_f32_e32 v0, v233, v0
	s_nop 2
	v_cndmask_b32_e32 v48, v216, v48, vcc
	v_cmp_lt_i32_e32 vcc, v14, v226
	s_nop 1
	v_cndmask_b32_e32 v65, v216, v97, vcc
	v_cmp_le_i32_e32 vcc, v14, v226
	v_or_b32_e32 v14, 0xe1, v224
	s_nop 0
	v_cndmask_b32_e32 v64, v216, v96, vcc
	v_cmp_le_i32_e32 vcc, v14, v226
	v_or_b32_e32 v14, 0xc2, v224
	v_max_f32_e32 v15, v64, v64
	v_cndmask_b32_e32 v49, v216, v49, vcc
	v_cmp_le_i32_e32 vcc, v14, v226
	v_or_b32_e32 v14, 0xe2, v224
	s_nop 0
	v_cndmask_b32_e32 v66, v216, v98, vcc
	v_cmp_le_i32_e32 vcc, v14, v226
	v_or_b32_e32 v14, 0xc3, v224
	s_nop 0
	v_cndmask_b32_e32 v50, v216, v50, vcc
	v_cmp_le_i32_e32 vcc, v14, v226
	v_or_b32_e32 v14, 0xe3, v224
	s_nop 0
	v_cndmask_b32_e32 v67, v216, v99, vcc
	v_cmp_le_i32_e32 vcc, v14, v226
	v_or_b32_e32 v14, 0xc8, v224
	s_nop 0
	v_cndmask_b32_e32 v51, v216, v51, vcc
	v_cmp_le_i32_e32 vcc, v14, v226
	v_or_b32_e32 v14, 0xe8, v224
	s_nop 0
	v_cndmask_b32_e32 v68, v216, v100, vcc
	v_cmp_le_i32_e32 vcc, v14, v226
	v_or_b32_e32 v14, 0xc9, v224
	s_nop 0
	v_cndmask_b32_e32 v52, v216, v52, vcc
	v_cmp_le_i32_e32 vcc, v14, v226
	v_or_b32_e32 v14, 0xe9, v224
	s_nop 0
	v_cndmask_b32_e32 v69, v216, v101, vcc
	v_cmp_le_i32_e32 vcc, v14, v226
	v_or_b32_e32 v14, 0xca, v224
	s_nop 0
	v_cndmask_b32_e32 v53, v216, v53, vcc
	v_cmp_le_i32_e32 vcc, v14, v226
	v_or_b32_e32 v14, 0xea, v224
	s_nop 0
	v_cndmask_b32_e32 v70, v216, v102, vcc
	v_cmp_le_i32_e32 vcc, v14, v226
	v_or_b32_e32 v14, 0xcb, v224
	s_nop 0
	v_cndmask_b32_e32 v54, v216, v54, vcc
	v_cmp_le_i32_e32 vcc, v14, v226
	v_or_b32_e32 v14, 0xeb, v224
	s_nop 0
	v_cndmask_b32_e32 v71, v216, v103, vcc
	v_cmp_le_i32_e32 vcc, v14, v226
	v_or_b32_e32 v14, 0xd0, v224
	s_nop 0
	v_cndmask_b32_e32 v55, v216, v55, vcc
	v_cmp_le_i32_e32 vcc, v14, v226
	v_or_b32_e32 v14, 0xf0, v224
	s_nop 0
	v_cndmask_b32_e32 v72, v216, v104, vcc
	v_cmp_le_i32_e32 vcc, v14, v226
	v_or_b32_e32 v14, 0xd1, v224
	s_nop 0
	v_cndmask_b32_e32 v56, v216, v56, vcc
	v_cmp_le_i32_e32 vcc, v14, v226
	v_or_b32_e32 v14, 0xf1, v224
	s_nop 0
	v_cndmask_b32_e32 v73, v216, v105, vcc
	v_cmp_le_i32_e32 vcc, v14, v226
	v_or_b32_e32 v14, 0xd2, v224
	s_nop 0
	v_cndmask_b32_e32 v57, v216, v57, vcc
	v_cmp_le_i32_e32 vcc, v14, v226
	v_or_b32_e32 v14, 0xf2, v224
	s_nop 0
	v_cndmask_b32_e32 v74, v216, v106, vcc
	v_cmp_le_i32_e32 vcc, v14, v226
	v_or_b32_e32 v14, 0xd3, v224
	s_nop 0
	v_cndmask_b32_e32 v58, v216, v58, vcc
	v_cmp_le_i32_e32 vcc, v14, v226
	v_or_b32_e32 v14, 0xf3, v224
	s_nop 0
	v_cndmask_b32_e32 v75, v216, v107, vcc
	v_cmp_le_i32_e32 vcc, v14, v226
	v_or_b32_e32 v14, 0xd8, v224
	s_nop 0
	v_cndmask_b32_e32 v59, v216, v59, vcc
	v_cmp_le_i32_e32 vcc, v14, v226
	v_or_b32_e32 v14, 0xf8, v224
	s_nop 0
	v_cndmask_b32_e32 v76, v216, v108, vcc
	v_cmp_le_i32_e32 vcc, v14, v226
	v_or_b32_e32 v14, 0xd9, v224
	s_nop 0
	v_cndmask_b32_e32 v60, v216, v60, vcc
	v_cmp_le_i32_e32 vcc, v14, v226
	v_or_b32_e32 v14, 0xf9, v224
	s_nop 0
	v_cndmask_b32_e32 v77, v216, v109, vcc
	v_cmp_le_i32_e32 vcc, v14, v226
	v_or_b32_e32 v14, 0xda, v224
	s_nop 0
	v_cndmask_b32_e32 v61, v216, v61, vcc
	v_cmp_le_i32_e32 vcc, v14, v226
	v_or_b32_e32 v14, 0xfa, v224
	s_nop 0
	v_cndmask_b32_e32 v78, v216, v110, vcc
	v_cmp_le_i32_e32 vcc, v14, v226
	v_or_b32_e32 v14, 0xdb, v224
	s_nop 0
	v_cndmask_b32_e32 v62, v216, v62, vcc
	v_cmp_le_i32_e32 vcc, v14, v226
	v_or_b32_e32 v14, 0xfb, v224
	s_nop 0
	v_cndmask_b32_e32 v79, v216, v111, vcc
	v_cmp_le_i32_e32 vcc, v14, v226
	v_max_f32_e32 v14, v65, v65
	v_max_f32_e32 v14, v15, v14
	v_max3_f32 v15, v66, v67, v49
	v_max3_f32 v14, v14, v48, v50
	v_max3_f32 v14, v14, v51, v68
	v_max3_f32 v15, v15, v70, v71
	v_max3_f32 v14, v14, v69, v52
	v_max3_f32 v15, v15, v54, v55
	v_max3_f32 v14, v14, v53, v72
	v_max3_f32 v15, v15, v74, v75
	v_max3_f32 v14, v14, v73, v56
	v_max3_f32 v15, v15, v58, v59
	v_cndmask_b32_e32 v63, v216, v63, vcc
	v_max3_f32 v14, v14, v57, v76
	v_max3_f32 v15, v15, v78, v79
	v_max3_f32 v14, v14, v77, v60
	v_max3_f32 v15, v15, v62, v63
	v_max3_f32 v14, v14, v61, v15
	v_mov_b32_e32 v15, v14
	s_nop 1
	v_permlane32_swap_b32_e32 v14, v15
	v_max_f32_e32 v14, v14, v15
	v_cmp_lt_f32_e32 vcc, s49, v14
	s_cmp_lg_u64 vcc, 0
	s_cselect_b64 s[4:5], -1, 0
	s_cbranch_vccnz .LBB0_2843

.LBB0_2511:
	v_add_f32_e32 v15, v233, v14
	v_max_f32_e32 v14, v112, v113
	v_max3_f32 v76, v114, v115, v97
	v_max3_f32 v14, v14, v96, v98
	v_max3_f32 v14, v14, v99, v116
	v_max3_f32 v76, v76, v118, v119
	v_max3_f32 v14, v14, v117, v100
	v_max3_f32 v76, v76, v102, v103
	v_max3_f32 v14, v14, v101, v120
	v_max3_f32 v76, v76, v122, v123
	v_max3_f32 v14, v14, v121, v104
	v_max3_f32 v76, v76, v106, v107
	v_max3_f32 v14, v14, v105, v124
	v_max3_f32 v76, v76, v126, v127
	v_max3_f32 v14, v14, v125, v108
	v_max3_f32 v76, v76, v110, v111
	v_max3_f32 v14, v14, v109, v76
	v_mov_b32_e32 v76, v14
	s_nop 1
	v_permlane32_swap_b32_e32 v14, v76
	v_max_f32_e32 v14, v14, v76
	v_cmp_lt_f32_e32 vcc, s49, v14
	s_cmp_lg_u64 vcc, 0
	s_cselect_b64 s[6:7], -1, 0
	s_cbranch_vccnz .LBB0_2549

.LBB0_2526:
	v_add_f32_e32 v233, v15, v96
	v_max_f32_e32 v15, v80, v81
	v_max3_f32 v96, v82, v83, v65
	v_max3_f32 v15, v15, v64, v66
	v_max3_f32 v15, v15, v67, v84
	v_max3_f32 v96, v96, v86, v87
	v_max3_f32 v15, v15, v85, v68
	v_max3_f32 v96, v96, v70, v71
	v_max3_f32 v15, v15, v69, v88
	v_max3_f32 v96, v96, v90, v91
	v_max3_f32 v15, v15, v89, v72
	v_max3_f32 v96, v96, v74, v75
	v_max3_f32 v15, v15, v73, v92
	v_max3_f32 v96, v96, v94, v95
	v_max3_f32 v15, v15, v93, v76
	v_max3_f32 v96, v96, v78, v79
	v_max3_f32 v15, v15, v77, v96
	v_mov_b32_e32 v96, v15
	s_nop 1
	v_permlane32_swap_b32_e32 v15, v96
	v_max_f32_e32 v15, v15, v96
	v_cmp_lt_f32_e32 vcc, s49, v15
	s_cmp_lg_u64 vcc, 0
	s_cselect_b64 s[22:23], -1, 0
	s_cbranch_vccnz .LBB0_2552
